# one workgroup per XCD issues an early asynchronous L2 write-back at each phase seam
# baseline (speedup 1.0000x reference)
.LBB0_81:
	s_cmp_gt_i32 s77, 1
	s_cselect_b64 s[2:3], -1, 0
	s_and_b64 s[0:1], s[12:13], s[2:3]
	s_andn2_b64 vcc, exec, s[0:1]
	s_cbranch_vccnz .LBB0_135
	s_waitcnt vmcnt(0)
	s_barrier
	v_readfirstlane_b32 s0, v188
	s_lshr_b32 s0, s0, 6
	s_cmp_eq_u32 s0, 1
	s_cbranch_scc0 .Lwb_skip1
	s_lshr_b32 s0, s33, 3
	s_cmp_eq_u32 s0, 0
	s_cbranch_scc0 .Lwb_skip1
	buffer_wbl2 sc1
.Lwb_skip1:
	s_mov_b64 s[4:5], exec
	v_readlane_b32 s0, v250, 1
	v_readlane_b32 s1, v250, 2
	s_and_b64 s[0:1], s[4:5], s[0:1]
	s_mov_b64 exec, s[0:1]
	s_cbranch_execz .LBB0_134
	s_add_i32 s0, 0, 0x20000
	v_mov_b32_e32 v0, s0
	s_waitcnt vmcnt(0) expcnt(0) lgkmcnt(0)
	ds_read_b32 v2, v0
	s_add_i32 s0, 0, 0x20004
	v_mov_b32_e32 v0, s0
	ds_read_b32 v0, v0
	s_waitcnt lgkmcnt(1)
	v_cmp_ne_u32_e32 vcc, 0, v2
	s_cbranch_vccnz .LBB0_98
	s_add_u32 s6, s74, 0x1200
	s_addc_u32 s7, s75, 0
	s_add_u32 s8, s74, 0x1400
	s_addc_u32 s9, s75, 0
	s_add_u32 s10, s74, 0x1500
	s_addc_u32 s11, s75, 0
	s_add_u32 s12, s74, 0x1600
	s_addc_u32 s13, s75, 0
	s_add_u32 s14, s74, 0x1700
	s_addc_u32 s15, s75, 0
	s_add_u32 s16, s74, 0x1800
	s_addc_u32 s17, s75, 0
	s_add_u32 s18, s74, 0x1900
	s_addc_u32 s19, s75, 0
	s_add_u32 s20, s74, 0x1a00
	s_addc_u32 s21, s75, 0
	s_add_u32 s22, s74, 0x1b00
	s_addc_u32 s23, s75, 0
	s_add_u32 s24, s74, 0x1c00
	s_addc_u32 s25, s75, 0
	s_add_u32 s26, s74, 0x1d00
	s_addc_u32 s27, s75, 0
	s_add_u32 s28, s74, 0x1e00
	s_addc_u32 s29, s75, 0
	s_add_u32 s30, s74, 0x1f00
	s_addc_u32 s31, s75, 0
	s_add_u32 s34, s74, 0x2000
	s_addc_u32 s35, s75, 0
	s_add_u32 s36, s74, 0x2100
	s_addc_u32 s37, s75, 0
	s_add_u32 s42, s74, 0x2200
	v_readlane_b32 s0, v250, 0
	s_addc_u32 s43, s75, 0
	s_mul_i32 s0, s79, s0
	s_add_u32 s46, s74, 0x2300
	s_mul_i32 s0, s0, s78
	s_addc_u32 s47, s75, 0
	s_mov_b32 s1, 1
	v_mov_b32_e32 v16, 0
	s_branch .LBB0_86

.Lp1_done:
.LBB0_145:
	s_cmp_gt_i32 s77, 2
	s_cselect_b64 s[2:3], -1, 0
	s_and_b64 s[0:1], s[4:5], s[2:3]
	s_andn2_b64 vcc, exec, s[0:1]
	s_cbranch_vccnz .LBB0_199
	s_waitcnt vmcnt(0)
	s_barrier
	v_readfirstlane_b32 s0, v188
	s_lshr_b32 s0, s0, 6
	s_cmp_eq_u32 s0, 1
	s_cbranch_scc0 .Lwb_skip2
	s_lshr_b32 s0, s33, 3
	s_cmp_eq_u32 s0, 0
	s_cbranch_scc0 .Lwb_skip2
	buffer_wbl2 sc1
.Lwb_skip2:
	s_mov_b64 s[4:5], exec
	v_readlane_b32 s0, v250, 1
	v_readlane_b32 s1, v250, 2
	s_and_b64 s[0:1], s[4:5], s[0:1]
	s_mov_b64 exec, s[0:1]
	s_cbranch_execz .LBB0_198
	s_add_i32 s0, 0, 0x20000
	v_mov_b32_e32 v0, s0
	s_waitcnt vmcnt(0) expcnt(0) lgkmcnt(0)
	ds_read_b32 v2, v0
	s_add_i32 s0, 0, 0x20004
	v_mov_b32_e32 v0, s0
	ds_read_b32 v0, v0
	s_waitcnt lgkmcnt(1)
	v_cmp_ne_u32_e32 vcc, 0, v2
	s_cbranch_vccnz .LBB0_162
	s_add_u32 s6, s74, 0x1200
	s_addc_u32 s7, s75, 0
	s_add_u32 s8, s74, 0x1400
	s_addc_u32 s9, s75, 0
	s_add_u32 s10, s74, 0x1500
	s_addc_u32 s11, s75, 0
	s_add_u32 s12, s74, 0x1600
	s_addc_u32 s13, s75, 0
	s_add_u32 s14, s74, 0x1700
	s_addc_u32 s15, s75, 0
	s_add_u32 s16, s74, 0x1800
	s_addc_u32 s17, s75, 0
	s_add_u32 s18, s74, 0x1900
	s_addc_u32 s19, s75, 0
	s_add_u32 s20, s74, 0x1a00
	s_addc_u32 s21, s75, 0
	s_add_u32 s22, s74, 0x1b00
	s_addc_u32 s23, s75, 0
	s_add_u32 s24, s74, 0x1c00
	s_addc_u32 s25, s75, 0
	s_add_u32 s26, s74, 0x1d00
	s_addc_u32 s27, s75, 0
	s_add_u32 s28, s74, 0x1e00
	s_addc_u32 s29, s75, 0
	s_add_u32 s30, s74, 0x1f00
	s_addc_u32 s31, s75, 0
	s_add_u32 s34, s74, 0x2000
	s_addc_u32 s35, s75, 0
	s_add_u32 s36, s74, 0x2100
	s_addc_u32 s37, s75, 0
	s_add_u32 s42, s74, 0x2200
	v_readlane_b32 s0, v250, 0
	s_addc_u32 s43, s75, 0
	s_mul_i32 s0, s79, s0
	s_add_u32 s44, s74, 0x2300
	s_mul_i32 s0, s0, s78
	s_addc_u32 s45, s75, 0
	s_mov_b32 s1, 1
	v_mov_b32_e32 v16, 0
	s_branch .LBB0_150

.LBB0_230:
	s_cmp_gt_i32 s77, 3
	s_cselect_b64 s[2:3], -1, 0
	s_and_b64 s[0:1], s[4:5], s[2:3]
	s_andn2_b64 vcc, exec, s[0:1]
	s_cbranch_vccnz .LBB0_284
	s_waitcnt vmcnt(0)
	s_waitcnt vmcnt(0)
	s_barrier
	v_readfirstlane_b32 s0, v188
	s_lshr_b32 s0, s0, 6
	s_cmp_eq_u32 s0, 1
	s_cbranch_scc0 .Lwb_skip3
	s_lshr_b32 s0, s33, 3
	s_cmp_eq_u32 s0, 0
	s_cbranch_scc0 .Lwb_skip3
	buffer_wbl2 sc1

.LBB0_350:
	s_cmp_gt_i32 s77, 4
	s_cselect_b64 s[2:3], -1, 0
	s_and_b64 s[0:1], s[6:7], s[2:3]
	s_andn2_b64 vcc, exec, s[0:1]
	s_cbranch_vccnz .LBB0_404
	s_waitcnt vmcnt(0)
	s_waitcnt vmcnt(0)
	s_barrier
	v_readfirstlane_b32 s0, v188
	s_lshr_b32 s0, s0, 6
	s_cmp_eq_u32 s0, 1
	s_cbranch_scc0 .Lwb_skip4
	s_lshr_b32 s0, s33, 3
	s_cmp_eq_u32 s0, 0
	s_cbranch_scc0 .Lwb_skip4
	buffer_wbl2 sc1

.LBB0_448:
	s_cmp_gt_i32 s77, 5
	s_cselect_b64 s[2:3], -1, 0
	s_and_b64 s[0:1], s[6:7], s[2:3]
	s_andn2_b64 vcc, exec, s[0:1]
	s_cbranch_vccnz .LBB0_502
	s_waitcnt vmcnt(0)
	s_waitcnt vmcnt(0)
	s_barrier
	v_readfirstlane_b32 s0, v188
	s_lshr_b32 s0, s0, 6
	s_cmp_eq_u32 s0, 1
	s_cbranch_scc0 .Lwb_skip5
	s_lshr_b32 s0, s33, 3
	s_cmp_eq_u32 s0, 0
	s_cbranch_scc0 .Lwb_skip5
	buffer_wbl2 sc1

.LBB0_517:
	s_cmp_gt_i32 s77, 6
	s_cselect_b64 s[2:3], -1, 0
	s_and_b64 s[0:1], s[42:43], s[2:3]
	s_andn2_b64 vcc, exec, s[0:1]
	s_cbranch_vccnz .LBB0_571
	s_waitcnt vmcnt(0)
	s_waitcnt vmcnt(0)
	s_barrier
	v_readfirstlane_b32 s0, v188
	s_lshr_b32 s0, s0, 6
	s_cmp_eq_u32 s0, 1
	s_cbranch_scc0 .Lwb_skip6
	s_lshr_b32 s0, s33, 3
	s_cmp_eq_u32 s0, 0
	s_cbranch_scc0 .Lwb_skip6
	buffer_wbl2 sc1

.LBB0_614:
	s_cmp_gt_i32 s77, 7
	s_cselect_b64 s[2:3], -1, 0
	s_and_b64 s[0:1], s[6:7], s[2:3]
	s_andn2_b64 vcc, exec, s[0:1]
	s_cbranch_vccnz .LBB0_668
	s_waitcnt vmcnt(0)
	s_waitcnt vmcnt(0) lgkmcnt(0)
	s_barrier
	v_readfirstlane_b32 s0, v188
	s_lshr_b32 s0, s0, 6
	s_cmp_eq_u32 s0, 1
	s_cbranch_scc0 .Lwb_skip7
	s_lshr_b32 s0, s33, 3
	s_cmp_eq_u32 s0, 0
	s_cbranch_scc0 .Lwb_skip7
	buffer_wbl2 sc1
.Lwb_skip7:
	s_mov_b64 s[4:5], exec
	v_readlane_b32 s0, v250, 1
	v_readlane_b32 s1, v250, 2
	s_and_b64 s[0:1], s[4:5], s[0:1]
	s_mov_b64 exec, s[0:1]
	s_cbranch_execz .LBB0_667
	s_add_i32 s0, 0, 0x20000
	v_mov_b32_e32 v0, s0
	s_waitcnt vmcnt(0) expcnt(0) lgkmcnt(0)
	ds_read_b32 v2, v0
	s_add_i32 s0, 0, 0x20004
	v_mov_b32_e32 v0, s0
	ds_read_b32 v0, v0
	s_waitcnt lgkmcnt(1)
	v_cmp_ne_u32_e32 vcc, 0, v2
	s_cbranch_vccnz .LBB0_631
	s_add_u32 s6, s74, 0x1200
	s_addc_u32 s7, s75, 0
	s_add_u32 s8, s74, 0x1400
	s_addc_u32 s9, s75, 0
	s_add_u32 s10, s74, 0x1500
	s_addc_u32 s11, s75, 0
	s_add_u32 s12, s74, 0x1600
	s_addc_u32 s13, s75, 0
	s_add_u32 s14, s74, 0x1700
	s_addc_u32 s15, s75, 0
	s_add_u32 s16, s74, 0x1800
	s_addc_u32 s17, s75, 0
	s_add_u32 s18, s74, 0x1900
	s_addc_u32 s19, s75, 0
	s_add_u32 s20, s74, 0x1a00
	s_addc_u32 s21, s75, 0
	s_add_u32 s22, s74, 0x1b00
	s_addc_u32 s23, s75, 0
	s_add_u32 s24, s74, 0x1c00
	s_addc_u32 s25, s75, 0
	s_add_u32 s26, s74, 0x1d00
	s_addc_u32 s27, s75, 0
	s_add_u32 s28, s74, 0x1e00
	s_addc_u32 s29, s75, 0
	s_add_u32 s30, s74, 0x1f00
	s_addc_u32 s31, s75, 0
	s_add_u32 s34, s74, 0x2000
	s_addc_u32 s35, s75, 0
	s_add_u32 s36, s74, 0x2100
	s_addc_u32 s37, s75, 0
	s_add_u32 s40, s74, 0x2200
	v_readlane_b32 s0, v250, 0
	s_addc_u32 s41, s75, 0
	s_mul_i32 s0, s79, s0
	s_add_u32 s42, s74, 0x2300
	s_mul_i32 s0, s0, s78
	s_addc_u32 s43, s75, 0
	s_mov_b32 s1, 1
	v_mov_b32_e32 v16, 0
	s_branch .LBB0_619

.LBB0_685:
	s_cmp_gt_i32 s77, 8
	s_cselect_b64 s[2:3], -1, 0
	s_and_b64 s[0:1], s[4:5], s[2:3]
	s_andn2_b64 vcc, exec, s[0:1]
	s_cbranch_vccnz .LBB0_739
	s_waitcnt vmcnt(0)
	s_waitcnt vmcnt(0) lgkmcnt(0)
	s_barrier
	v_readfirstlane_b32 s0, v188
	s_lshr_b32 s0, s0, 6
	s_cmp_eq_u32 s0, 1
	s_cbranch_scc0 .Lwb_skip8
	s_lshr_b32 s0, s33, 3
	s_cmp_eq_u32 s0, 0
	s_cbranch_scc0 .Lwb_skip8
	buffer_wbl2 sc1
.Lwb_skip8:
	s_mov_b64 s[4:5], exec
	v_readlane_b32 s0, v250, 1
	v_readlane_b32 s1, v250, 2
	s_and_b64 s[0:1], s[4:5], s[0:1]
	s_mov_b64 exec, s[0:1]
	s_cbranch_execz .LBB0_738
	s_add_i32 s0, 0, 0x20000
	v_mov_b32_e32 v0, s0
	s_waitcnt vmcnt(0) expcnt(0) lgkmcnt(0)
	ds_read_b32 v2, v0
	s_add_i32 s0, 0, 0x20004
	v_mov_b32_e32 v0, s0
	ds_read_b32 v0, v0
	s_waitcnt lgkmcnt(1)
	v_cmp_ne_u32_e32 vcc, 0, v2
	s_cbranch_vccnz .LBB0_702
	v_readlane_b32 s0, v250, 0
	s_mul_i32 s38, s79, s0
	s_add_u32 s0, s74, 0x1200
	s_addc_u32 s1, s75, 0
	s_add_u32 s6, s74, 0x1400
	s_addc_u32 s7, s75, 0
	s_add_u32 s8, s74, 0x1500
	s_addc_u32 s9, s75, 0
	s_add_u32 s10, s74, 0x1600
	s_addc_u32 s11, s75, 0
	s_add_u32 s12, s74, 0x1700
	s_addc_u32 s13, s75, 0
	s_add_u32 s14, s74, 0x1800
	s_addc_u32 s15, s75, 0
	s_add_u32 s16, s74, 0x1900
	s_addc_u32 s17, s75, 0
	s_add_u32 s18, s74, 0x1a00
	s_addc_u32 s19, s75, 0
	s_add_u32 s20, s74, 0x1b00
	s_addc_u32 s21, s75, 0
	s_add_u32 s22, s74, 0x1c00
	s_addc_u32 s23, s75, 0
	s_add_u32 s24, s74, 0x1d00
	s_addc_u32 s25, s75, 0
	s_add_u32 s26, s74, 0x1e00
	s_addc_u32 s27, s75, 0
	s_add_u32 s28, s74, 0x1f00
	s_addc_u32 s29, s75, 0
	s_add_u32 s30, s74, 0x2000
	s_addc_u32 s31, s75, 0
	s_add_u32 s34, s74, 0x2100
	s_addc_u32 s35, s75, 0
	s_add_u32 s36, s74, 0x2200
	s_addc_u32 s37, s75, 0
	s_add_u32 s40, s74, 0x2300
	s_mul_i32 s38, s38, s78
	s_addc_u32 s41, s75, 0
	s_mov_b32 s39, 1
	v_mov_b32_e32 v16, 0
	s_branch .LBB0_690
